# v21 + W_in_even transpose loads issued together + leftover division helper instructions removed
# speedup vs baseline: 1.0023x; 1.0016x over previous
; __device__ __forceinline__ unsigned xb_add(unsigned* p, unsigned v) { return __hip_atomic_fetch_add(p, v, __ATOMIC_RELAXED, __HIP_MEMORY_SCOPE_AGENT); }
; __device__ __forceinline__ void xcd_barrier(const XcdBarrier& b) {
;     ...
;             __builtin_amdgcn_fence(__ATOMIC_ACQUIRE, "agent");
;             xb_add(&bar[XB_XGEN(b.x)], 1u);
;             asm volatile("s_waitcnt vmcnt(0)" ::: "memory");
.LBB0_2573:
	s_or_b64 exec, exec, s[6:7]
	s_mov_b64 s[6:7], exec
	v_mbcnt_lo_u32_b32 v0, s6, 0
	v_mbcnt_hi_u32_b32 v0, s7, v0
	v_cmp_eq_u32_e32 vcc, 0, v0
	s_waitcnt vmcnt(0)
	buffer_inv sc1
	s_and_saveexec_b64 s[8:9], vcc
	s_cbranch_execz .LBB0_2575
	s_bcnt1_i32_b64 s6, s[6:7]
	v_mov_b32_e32 v0, 0x2000
	v_mov_b32_e32 v1, s6
	global_atomic_add v0, v1, s[2:3] offset:1024
	s_nop 0
	s_nop 0
	s_nop 0
	s_nop 0
	s_nop 0
	s_nop 0
	s_nop 0
	s_nop 0
	s_nop 0
	s_nop 0
	s_nop 0
	s_nop 0
	s_nop 0
	s_nop 0
	s_nop 0
	s_nop 0
	s_nop 0
	s_nop 0
	s_nop 0
	s_nop 0
	s_nop 0
	s_nop 0
	s_nop 0
	s_nop 0
	s_nop 0
	s_nop 0
	s_nop 0
	s_nop 0
	s_nop 0
	s_nop 0
	s_nop 0
	s_nop 0
	s_nop 0
	s_nop 0
	s_nop 0
	s_nop 0
	s_nop 0
	s_nop 0
	s_nop 0
	s_nop 0
	s_nop 0
	s_nop 0
	s_nop 0
	s_nop 0
	s_nop 0
	s_nop 0
	s_nop 0
	s_nop 0
